# v18 + P3 step A: all 16 token-row loads of the 8 rounds issued up front, loop unrolled (8 dependent HBM rounds -> 1)
# baseline (speedup 1.0000x reference)
; __device__ __forceinline__ void phase3(const P3Args& A, unsigned char* lds, int tid, int wave, int lane) {
;     ...
;             const int task = tid + (rep & 7) * 512, tok = task >> 5, c8 = (task & 31) * 8, t = t0 + tok;
;             const u32x4 pc = *(const u32x4*)(A.Rb + (size_t)t * RW + 1536 + c8);
;             u32x4 pp = (u32x4){0u, 0u, 0u, 0u};
;             if (t % SEQ) pp = *(const u32x4*)(A.Rb + (size_t)(t - 1) * RW + 1536 + c8);
;             const f32x4 m0 = *(const f32x4*)(A.mu + 1536 + c8), m1 = *(const f32x4*)(A.mu + 1536 + c8 + 4);
;             const unsigned pcw[4] = {pc.x, pc.y, pc.z, pc.w}, ppw[4] = {pp.x, pp.y, pp.z, pp.w};
.LBB0_311:
	s_barrier
	global_load_dwordx4 v[0:3], v[112:113], off offset:16
	global_load_dwordx4 v[4:7], v[112:113], off
	s_lshl_b32 s37, s41, 7
	s_mov_b32 s6, 0
	v_mov_b32_e32 v192, v117
	v_ashrrev_i32_e32 v192, 5, v192
	v_add_u32_e32 v192, s37, v192
	v_mad_i64_i32 v[194:195], s[98:99], v192, s17, v[114:115]
	global_load_dwordx4 v[128:131], v[194:195], off offset:3072
	v_and_b32_e32 v193, 0xfff, v192
	v_mov_b32_e32 v132, 0
	v_mov_b32_e32 v133, 0
	v_mov_b32_e32 v134, 0
	v_mov_b32_e32 v135, 0
	v_cmp_ne_u32_e64 s[100:101], 0, v193
	s_and_saveexec_b64 s[98:99], s[100:101]
	v_add_u32_e32 v192, -1, v192
	v_mad_i64_i32 v[194:195], s[100:101], v192, s17, v[114:115]
	global_load_dwordx4 v[132:135], v[194:195], off offset:3072
	s_or_b64 exec, exec, s[98:99]
	v_add_u32_e32 v192, 0x200, v117
	v_ashrrev_i32_e32 v192, 5, v192
	v_add_u32_e32 v192, s37, v192
	v_mad_i64_i32 v[194:195], s[98:99], v192, s17, v[114:115]
	global_load_dwordx4 v[136:139], v[194:195], off offset:3072
	v_and_b32_e32 v193, 0xfff, v192
	v_mov_b32_e32 v140, 0
	v_mov_b32_e32 v141, 0
	v_mov_b32_e32 v142, 0
	v_mov_b32_e32 v143, 0
	v_cmp_ne_u32_e64 s[100:101], 0, v193
	s_and_saveexec_b64 s[98:99], s[100:101]
	v_add_u32_e32 v192, -1, v192
	v_mad_i64_i32 v[194:195], s[100:101], v192, s17, v[114:115]
	global_load_dwordx4 v[140:143], v[194:195], off offset:3072
	s_or_b64 exec, exec, s[98:99]
	v_add_u32_e32 v192, 0x400, v117
	v_ashrrev_i32_e32 v192, 5, v192
	v_add_u32_e32 v192, s37, v192
	v_mad_i64_i32 v[194:195], s[98:99], v192, s17, v[114:115]
	global_load_dwordx4 v[144:147], v[194:195], off offset:3072
	v_and_b32_e32 v193, 0xfff, v192
	v_mov_b32_e32 v148, 0
	v_mov_b32_e32 v149, 0
	v_mov_b32_e32 v150, 0
	v_mov_b32_e32 v151, 0
	v_cmp_ne_u32_e64 s[100:101], 0, v193
	s_and_saveexec_b64 s[98:99], s[100:101]
	v_add_u32_e32 v192, -1, v192
	v_mad_i64_i32 v[194:195], s[100:101], v192, s17, v[114:115]
	global_load_dwordx4 v[148:151], v[194:195], off offset:3072
	s_or_b64 exec, exec, s[98:99]
	v_add_u32_e32 v192, 0x600, v117
	v_ashrrev_i32_e32 v192, 5, v192
	v_add_u32_e32 v192, s37, v192
	v_mad_i64_i32 v[194:195], s[98:99], v192, s17, v[114:115]
	global_load_dwordx4 v[152:155], v[194:195], off offset:3072
	v_and_b32_e32 v193, 0xfff, v192
	v_mov_b32_e32 v156, 0
	v_mov_b32_e32 v157, 0
	v_mov_b32_e32 v158, 0
	v_mov_b32_e32 v159, 0
	v_cmp_ne_u32_e64 s[100:101], 0, v193
	s_and_saveexec_b64 s[98:99], s[100:101]
	v_add_u32_e32 v192, -1, v192
	v_mad_i64_i32 v[194:195], s[100:101], v192, s17, v[114:115]
	global_load_dwordx4 v[156:159], v[194:195], off offset:3072
	s_or_b64 exec, exec, s[98:99]
	v_add_u32_e32 v192, 0x800, v117
	v_ashrrev_i32_e32 v192, 5, v192
	v_add_u32_e32 v192, s37, v192
	v_mad_i64_i32 v[194:195], s[98:99], v192, s17, v[114:115]
	global_load_dwordx4 v[160:163], v[194:195], off offset:3072
	v_and_b32_e32 v193, 0xfff, v192
	v_mov_b32_e32 v164, 0
	v_mov_b32_e32 v165, 0
	v_mov_b32_e32 v166, 0
	v_mov_b32_e32 v167, 0
	v_cmp_ne_u32_e64 s[100:101], 0, v193
	s_and_saveexec_b64 s[98:99], s[100:101]
	v_add_u32_e32 v192, -1, v192
	v_mad_i64_i32 v[194:195], s[100:101], v192, s17, v[114:115]
	global_load_dwordx4 v[164:167], v[194:195], off offset:3072
	s_or_b64 exec, exec, s[98:99]
	v_add_u32_e32 v192, 0xa00, v117
	v_ashrrev_i32_e32 v192, 5, v192
	v_add_u32_e32 v192, s37, v192
	v_mad_i64_i32 v[194:195], s[98:99], v192, s17, v[114:115]
	global_load_dwordx4 v[168:171], v[194:195], off offset:3072
	v_and_b32_e32 v193, 0xfff, v192
	v_mov_b32_e32 v172, 0
	v_mov_b32_e32 v173, 0
	v_mov_b32_e32 v174, 0
	v_mov_b32_e32 v175, 0
	v_cmp_ne_u32_e64 s[100:101], 0, v193
	s_and_saveexec_b64 s[98:99], s[100:101]
	v_add_u32_e32 v192, -1, v192
	v_mad_i64_i32 v[194:195], s[100:101], v192, s17, v[114:115]
	global_load_dwordx4 v[172:175], v[194:195], off offset:3072
	s_or_b64 exec, exec, s[98:99]
	v_add_u32_e32 v192, 0xc00, v117
	v_ashrrev_i32_e32 v192, 5, v192
	v_add_u32_e32 v192, s37, v192
	v_mad_i64_i32 v[194:195], s[98:99], v192, s17, v[114:115]
	global_load_dwordx4 v[176:179], v[194:195], off offset:3072
	v_and_b32_e32 v193, 0xfff, v192
	v_mov_b32_e32 v180, 0
	v_mov_b32_e32 v181, 0
	v_mov_b32_e32 v182, 0
	v_mov_b32_e32 v183, 0
	v_cmp_ne_u32_e64 s[100:101], 0, v193
	s_and_saveexec_b64 s[98:99], s[100:101]
	v_add_u32_e32 v192, -1, v192
	v_mad_i64_i32 v[194:195], s[100:101], v192, s17, v[114:115]
	global_load_dwordx4 v[180:183], v[194:195], off offset:3072
	s_or_b64 exec, exec, s[98:99]
	v_add_u32_e32 v192, 0xe00, v117
	v_ashrrev_i32_e32 v192, 5, v192
	v_add_u32_e32 v192, s37, v192
	v_mad_i64_i32 v[194:195], s[98:99], v192, s17, v[114:115]
	global_load_dwordx4 v[184:187], v[194:195], off offset:3072
	v_and_b32_e32 v193, 0xfff, v192
	v_mov_b32_e32 v188, 0
	v_mov_b32_e32 v189, 0
	v_mov_b32_e32 v190, 0
	v_mov_b32_e32 v191, 0
	v_cmp_ne_u32_e64 s[100:101], 0, v193
	s_and_saveexec_b64 s[98:99], s[100:101]
	v_add_u32_e32 v192, -1, v192
	v_mad_i64_i32 v[194:195], s[100:101], v192, s17, v[114:115]
	global_load_dwordx4 v[188:191], v[194:195], off offset:3072
	s_or_b64 exec, exec, s[98:99]
; __device__ __forceinline__ float sigmoidf_(float x) { return __builtin_amdgcn_rcpf(1.0f + __expf(-x)); }
; __device__ __forceinline__ void phase3(const P3Args& A, unsigned char* lds, int tid, int wave, int lane) {
;     ...
;             const int task = tid + (rep & 7) * 512, tok = task >> 5, c8 = (task & 31) * 8, t = t0 + tok;
;             const u32x4 pc = *(const u32x4*)(A.Rb + (size_t)t * RW + 1536 + c8);
;             u32x4 pp = (u32x4){0u, 0u, 0u, 0u};
;             if (t % SEQ) pp = *(const u32x4*)(A.Rb + (size_t)(t - 1) * RW + 1536 + c8);
;             const f32x4 m0 = *(const f32x4*)(A.mu + 1536 + c8), m1 = *(const f32x4*)(A.mu + 1536 + c8 + 4);
;             const unsigned pcw[4] = {pc.x, pc.y, pc.z, pc.w}, ppw[4] = {pp.x, pp.y, pp.z, pp.w};
;             float x[8];
; #pragma unroll
;             for (int i = 0; i < 4; ++i) {
;                 const float c_lo = __uint_as_float(pcw[i] << 16), c_hi = __uint_as_float(pcw[i] & 0xffff0000u), p_lo = __uint_as_float(ppw[i] << 16), p_hi = __uint_as_float(ppw[i] & 0xffff0000u);
;                 const float mlo = (i < 2) ? m0[2 * i] : m1[2 * i - 4], mhi = (i < 2) ? m0[2 * i + 1] : m1[2 * i - 3];
;                 x[2 * i] = c_lo + (p_lo - c_lo) * mlo; x[2 * i + 1] = c_hi + (p_hi - c_hi) * mhi;
;             }
;             if (c8 < 64) {
; #pragma unroll
;                 for (int i = 0; i < 8; ++i) { const float e = __expf(-2.0f * fabsf(x[i])); const float th = (1.0f - e) * __builtin_amdgcn_rcpf(1.0f + e); x[i] = copysignf(th, x[i]); }
;             } else if (c8 >= 128) {
; #pragma unroll
;                 for (int i = 0; i < 8; ++i) x[i] = sigmoidf_(x[i]);
;             }
.Lp3a_r0:
	v_mov_b32_e32 v8, v117
	v_ashrrev_i32_e32 v18, 5, v8
	s_waitcnt vmcnt(14)
	v_mov_b32_e32 v8, v128
	v_mov_b32_e32 v9, v129
	v_mov_b32_e32 v10, v130
	v_mov_b32_e32 v11, v131
	v_mov_b32_e32 v12, v132
	v_mov_b32_e32 v13, v133
	v_mov_b32_e32 v14, v134
	v_mov_b32_e32 v15, v135
	v_lshlrev_b32_e32 v16, 16, v8
	v_and_b32_e32 v17, 0xffff0000, v8
	v_lshlrev_b32_e32 v20, 16, v12
	v_and_b32_e32 v21, 0xffff0000, v12
	v_lshlrev_b32_e32 v8, 16, v9
	v_and_b32_e32 v9, 0xffff0000, v9
	v_lshlrev_b32_e32 v12, 16, v13
	v_and_b32_e32 v13, 0xffff0000, v13
	v_pk_add_f32 v[20:21], v[20:21], v[16:17] neg_lo:[0,1] neg_hi:[0,1]
	v_pk_add_f32 v[12:13], v[12:13], v[8:9] neg_lo:[0,1] neg_hi:[0,1]
	v_pk_fma_f32 v[16:17], v[4:5], v[20:21], v[16:17]
	v_pk_fma_f32 v[8:9], v[6:7], v[12:13], v[8:9]
	v_lshlrev_b32_e32 v12, 16, v10
	v_and_b32_e32 v13, 0xffff0000, v10
	v_lshlrev_b32_e32 v20, 16, v14
	v_and_b32_e32 v21, 0xffff0000, v14
	v_lshlrev_b32_e32 v10, 16, v11
	v_and_b32_e32 v11, 0xffff0000, v11
	v_lshlrev_b32_e32 v14, 16, v15
	v_and_b32_e32 v15, 0xffff0000, v15
	v_pk_add_f32 v[20:21], v[20:21], v[12:13] neg_lo:[0,1] neg_hi:[0,1]
	v_pk_add_f32 v[14:15], v[14:15], v[10:11] neg_lo:[0,1] neg_hi:[0,1]
	v_pk_fma_f32 v[12:13], v[0:1], v[20:21], v[12:13]
	v_pk_fma_f32 v[10:11], v[2:3], v[14:15], v[10:11]
	s_and_saveexec_b64 s[0:1], vcc
	s_xor_b64 s[0:1], exec, s[0:1]
	s_cbranch_execz .Lp3a_319_r0
	s_mov_b64 s[4:5], exec
	v_readlane_b32 s8, v241, 61
	v_readlane_b32 s9, v241, 62
	s_and_b64 s[8:9], s[4:5], s[8:9]
	s_mov_b64 exec, s[8:9]
	s_cbranch_execz .Lp3a_318_r0
	v_mul_f32_e32 v14, 0xbfb8aa3b, v16
	v_mul_f32_e32 v15, 0xbfb8aa3b, v17
	v_mul_f32_e32 v8, 0xbfb8aa3b, v8
	v_mul_f32_e32 v9, 0xbfb8aa3b, v9
	v_mul_f32_e32 v12, 0xbfb8aa3b, v12
	v_mul_f32_e32 v13, 0xbfb8aa3b, v13
	v_mul_f32_e32 v10, 0xbfb8aa3b, v10
	v_mul_f32_e32 v11, 0xbfb8aa3b, v11
	v_exp_f32_e32 v14, v14
	v_exp_f32_e32 v15, v15
	v_exp_f32_e32 v8, v8
	v_exp_f32_e32 v9, v9
	v_exp_f32_e32 v12, v12
	v_exp_f32_e32 v13, v13
	v_exp_f32_e32 v10, v10
	v_exp_f32_e32 v11, v11
	v_add_f32_e32 v14, 1.0, v14
	v_add_f32_e32 v15, 1.0, v15
	v_add_f32_e32 v8, 1.0, v8
	v_add_f32_e32 v9, 1.0, v9
	v_add_f32_e32 v12, 1.0, v12
	v_add_f32_e32 v13, 1.0, v13
	v_add_f32_e32 v10, 1.0, v10
	v_add_f32_e32 v11, 1.0, v11
	v_rcp_f32_e32 v16, v14
	v_rcp_f32_e32 v17, v15
	v_rcp_f32_e32 v8, v8
	v_rcp_f32_e32 v9, v9
	v_rcp_f32_e32 v12, v12
	v_rcp_f32_e32 v13, v13
	v_rcp_f32_e32 v10, v10
	v_rcp_f32_e32 v11, v11

; __device__ __forceinline__ unsigned pk2(float lo, float hi) { f32x2_t v = {lo, hi}; bf16x2_t b = __builtin_convertvector(v, bf16x2_t); return __builtin_bit_cast(unsigned, b); }
; __device__ __forceinline__ float sigmoidf_(float x) { return __builtin_amdgcn_rcpf(1.0f + __expf(-x)); }
; __device__ __forceinline__ void phase3(const P3Args& A, unsigned char* lds, int tid, int wave, int lane) {
;     ...
;             const int task = tid + (rep & 7) * 512, tok = task >> 5, c8 = (task & 31) * 8, t = t0 + tok;
;             const u32x4 pc = *(const u32x4*)(A.Rb + (size_t)t * RW + 1536 + c8);
;             u32x4 pp = (u32x4){0u, 0u, 0u, 0u};
;             if (t % SEQ) pp = *(const u32x4*)(A.Rb + (size_t)(t - 1) * RW + 1536 + c8);
;             const f32x4 m0 = *(const f32x4*)(A.mu + 1536 + c8), m1 = *(const f32x4*)(A.mu + 1536 + c8 + 4);
;             const unsigned pcw[4] = {pc.x, pc.y, pc.z, pc.w}, ppw[4] = {pp.x, pp.y, pp.z, pp.w};
;             float x[8];
; #pragma unroll
;             for (int i = 0; i < 4; ++i) {
;                 const float c_lo = __uint_as_float(pcw[i] << 16), c_hi = __uint_as_float(pcw[i] & 0xffff0000u), p_lo = __uint_as_float(ppw[i] << 16), p_hi = __uint_as_float(ppw[i] & 0xffff0000u);
;                 const float mlo = (i < 2) ? m0[2 * i] : m1[2 * i - 4], mhi = (i < 2) ? m0[2 * i + 1] : m1[2 * i - 3];
;                 x[2 * i] = c_lo + (p_lo - c_lo) * mlo; x[2 * i + 1] = c_hi + (p_hi - c_hi) * mhi;
;             }
;             if (c8 < 64) {
; #pragma unroll
;                 for (int i = 0; i < 8; ++i) { const float e = __expf(-2.0f * fabsf(x[i])); const float th = (1.0f - e) * __builtin_amdgcn_rcpf(1.0f + e); x[i] = copysignf(th, x[i]); }
;             } else if (c8 >= 128) {
; #pragma unroll
;                 for (int i = 0; i < 8; ++i) x[i] = sigmoidf_(x[i]);
;             }
;             *(u32x4*)(ACT + tok * AST + c8) = (u32x4){pk2(x[0], x[1]), pk2(x[2], x[3]), pk2(x[4], x[5]), pk2(x[6], x[7])};
.Lp3a_312_r0:
	s_or_b64 exec, exec, s[0:1]
	s_addk_i32 s6, 0x200
	v_cvt_pk_bf16_f32 v14, v16, v17
	v_cvt_pk_bf16_f32 v15, v8, v9
	v_cvt_pk_bf16_f32 v16, v12, v13
	v_cvt_pk_bf16_f32 v17, v10, v11
	v_mad_u64_u32 v[8:9], s[0:1], v18, s90, v[108:109]
	ds_write_b128 v8, v[14:17]
.Lp3a_r1:
	v_add_u32_e32 v8, 0x200, v117
	v_ashrrev_i32_e32 v18, 5, v8
	s_waitcnt vmcnt(12)
	v_mov_b32_e32 v8, v136
	v_mov_b32_e32 v9, v137
	v_mov_b32_e32 v10, v138
	v_mov_b32_e32 v11, v139
	v_mov_b32_e32 v12, v140
	v_mov_b32_e32 v13, v141
	v_mov_b32_e32 v14, v142
	v_mov_b32_e32 v15, v143
	v_lshlrev_b32_e32 v16, 16, v8
	v_and_b32_e32 v17, 0xffff0000, v8
	v_lshlrev_b32_e32 v20, 16, v12
	v_and_b32_e32 v21, 0xffff0000, v12
	v_lshlrev_b32_e32 v8, 16, v9
	v_and_b32_e32 v9, 0xffff0000, v9
	v_lshlrev_b32_e32 v12, 16, v13
	v_and_b32_e32 v13, 0xffff0000, v13
	v_pk_add_f32 v[20:21], v[20:21], v[16:17] neg_lo:[0,1] neg_hi:[0,1]
	v_pk_add_f32 v[12:13], v[12:13], v[8:9] neg_lo:[0,1] neg_hi:[0,1]
	v_pk_fma_f32 v[16:17], v[4:5], v[20:21], v[16:17]
	v_pk_fma_f32 v[8:9], v[6:7], v[12:13], v[8:9]
	v_lshlrev_b32_e32 v12, 16, v10
	v_and_b32_e32 v13, 0xffff0000, v10
	v_lshlrev_b32_e32 v20, 16, v14
	v_and_b32_e32 v21, 0xffff0000, v14
	v_lshlrev_b32_e32 v10, 16, v11
	v_and_b32_e32 v11, 0xffff0000, v11
	v_lshlrev_b32_e32 v14, 16, v15
	v_and_b32_e32 v15, 0xffff0000, v15
	v_pk_add_f32 v[20:21], v[20:21], v[12:13] neg_lo:[0,1] neg_hi:[0,1]
	v_pk_add_f32 v[14:15], v[14:15], v[10:11] neg_lo:[0,1] neg_hi:[0,1]
	v_pk_fma_f32 v[12:13], v[0:1], v[20:21], v[12:13]
	v_pk_fma_f32 v[10:11], v[2:3], v[14:15], v[10:11]
	s_and_saveexec_b64 s[0:1], vcc
	s_xor_b64 s[0:1], exec, s[0:1]
	s_cbranch_execz .Lp3a_319_r1
	s_mov_b64 s[4:5], exec
	v_readlane_b32 s8, v241, 61
	v_readlane_b32 s9, v241, 62
	s_and_b64 s[8:9], s[4:5], s[8:9]
	s_mov_b64 exec, s[8:9]
	s_cbranch_execz .Lp3a_318_r1
	v_mul_f32_e32 v14, 0xbfb8aa3b, v16
	v_mul_f32_e32 v15, 0xbfb8aa3b, v17
	v_mul_f32_e32 v8, 0xbfb8aa3b, v8
	v_mul_f32_e32 v9, 0xbfb8aa3b, v9
	v_mul_f32_e32 v12, 0xbfb8aa3b, v12
	v_mul_f32_e32 v13, 0xbfb8aa3b, v13
	v_mul_f32_e32 v10, 0xbfb8aa3b, v10
	v_mul_f32_e32 v11, 0xbfb8aa3b, v11
	v_exp_f32_e32 v14, v14
	v_exp_f32_e32 v15, v15
	v_exp_f32_e32 v8, v8
	v_exp_f32_e32 v9, v9
	v_exp_f32_e32 v12, v12
	v_exp_f32_e32 v13, v13
	v_exp_f32_e32 v10, v10
	v_exp_f32_e32 v11, v11
	v_add_f32_e32 v14, 1.0, v14
	v_add_f32_e32 v15, 1.0, v15
	v_add_f32_e32 v8, 1.0, v8
	v_add_f32_e32 v9, 1.0, v9
	v_add_f32_e32 v12, 1.0, v12
	v_add_f32_e32 v13, 1.0, v13
	v_add_f32_e32 v10, 1.0, v10
	v_add_f32_e32 v11, 1.0, v11
	v_rcp_f32_e32 v16, v14
	v_rcp_f32_e32 v17, v15
	v_rcp_f32_e32 v8, v8
	v_rcp_f32_e32 v9, v9
	v_rcp_f32_e32 v12, v12
	v_rcp_f32_e32 v13, v13
	v_rcp_f32_e32 v10, v10
	v_rcp_f32_e32 v11, v11

; __device__ __forceinline__ float sigmoidf_(float x) { return __builtin_amdgcn_rcpf(1.0f + __expf(-x)); }
; __device__ __forceinline__ void phase3(const P3Args& A, unsigned char* lds, int tid, int wave, int lane) {
;     ...
;             const int task = tid + (rep & 7) * 512, tok = task >> 5, c8 = (task & 31) * 8, t = t0 + tok;
;             const u32x4 pc = *(const u32x4*)(A.Rb + (size_t)t * RW + 1536 + c8);
;             u32x4 pp = (u32x4){0u, 0u, 0u, 0u};
;             if (t % SEQ) pp = *(const u32x4*)(A.Rb + (size_t)(t - 1) * RW + 1536 + c8);
;             const f32x4 m0 = *(const f32x4*)(A.mu + 1536 + c8), m1 = *(const f32x4*)(A.mu + 1536 + c8 + 4);
;             const unsigned pcw[4] = {pc.x, pc.y, pc.z, pc.w}, ppw[4] = {pp.x, pp.y, pp.z, pp.w};
;             float x[8];
; #pragma unroll
;             for (int i = 0; i < 4; ++i) {
;                 const float c_lo = __uint_as_float(pcw[i] << 16), c_hi = __uint_as_float(pcw[i] & 0xffff0000u), p_lo = __uint_as_float(ppw[i] << 16), p_hi = __uint_as_float(ppw[i] & 0xffff0000u);
;                 const float mlo = (i < 2) ? m0[2 * i] : m1[2 * i - 4], mhi = (i < 2) ? m0[2 * i + 1] : m1[2 * i - 3];
;                 x[2 * i] = c_lo + (p_lo - c_lo) * mlo; x[2 * i + 1] = c_hi + (p_hi - c_hi) * mhi;
;             }
;             if (c8 < 64) {
; #pragma unroll
;                 for (int i = 0; i < 8; ++i) { const float e = __expf(-2.0f * fabsf(x[i])); const float th = (1.0f - e) * __builtin_amdgcn_rcpf(1.0f + e); x[i] = copysignf(th, x[i]); }
;             } else if (c8 >= 128) {
; #pragma unroll
;                 for (int i = 0; i < 8; ++i) x[i] = sigmoidf_(x[i]);
;             }
.Lp3a_r2:
	v_add_u32_e32 v8, 0x400, v117
	v_ashrrev_i32_e32 v18, 5, v8
	s_waitcnt vmcnt(10)
	v_mov_b32_e32 v8, v144
	v_mov_b32_e32 v9, v145
	v_mov_b32_e32 v10, v146
	v_mov_b32_e32 v11, v147
	v_mov_b32_e32 v12, v148
	v_mov_b32_e32 v13, v149
	v_mov_b32_e32 v14, v150
	v_mov_b32_e32 v15, v151
	v_lshlrev_b32_e32 v16, 16, v8
	v_and_b32_e32 v17, 0xffff0000, v8
	v_lshlrev_b32_e32 v20, 16, v12
	v_and_b32_e32 v21, 0xffff0000, v12
	v_lshlrev_b32_e32 v8, 16, v9
	v_and_b32_e32 v9, 0xffff0000, v9
	v_lshlrev_b32_e32 v12, 16, v13
	v_and_b32_e32 v13, 0xffff0000, v13
	v_pk_add_f32 v[20:21], v[20:21], v[16:17] neg_lo:[0,1] neg_hi:[0,1]
	v_pk_add_f32 v[12:13], v[12:13], v[8:9] neg_lo:[0,1] neg_hi:[0,1]
	v_pk_fma_f32 v[16:17], v[4:5], v[20:21], v[16:17]
	v_pk_fma_f32 v[8:9], v[6:7], v[12:13], v[8:9]
	v_lshlrev_b32_e32 v12, 16, v10
	v_and_b32_e32 v13, 0xffff0000, v10
	v_lshlrev_b32_e32 v20, 16, v14
	v_and_b32_e32 v21, 0xffff0000, v14
	v_lshlrev_b32_e32 v10, 16, v11
	v_and_b32_e32 v11, 0xffff0000, v11
	v_lshlrev_b32_e32 v14, 16, v15
	v_and_b32_e32 v15, 0xffff0000, v15
	v_pk_add_f32 v[20:21], v[20:21], v[12:13] neg_lo:[0,1] neg_hi:[0,1]
	v_pk_add_f32 v[14:15], v[14:15], v[10:11] neg_lo:[0,1] neg_hi:[0,1]
	v_pk_fma_f32 v[12:13], v[0:1], v[20:21], v[12:13]
	v_pk_fma_f32 v[10:11], v[2:3], v[14:15], v[10:11]
	s_and_saveexec_b64 s[0:1], vcc
	s_xor_b64 s[0:1], exec, s[0:1]
	s_cbranch_execz .Lp3a_319_r2
	s_mov_b64 s[4:5], exec
	v_readlane_b32 s8, v241, 61
	v_readlane_b32 s9, v241, 62
	s_and_b64 s[8:9], s[4:5], s[8:9]
	s_mov_b64 exec, s[8:9]
	s_cbranch_execz .Lp3a_318_r2
	v_mul_f32_e32 v14, 0xbfb8aa3b, v16
	v_mul_f32_e32 v15, 0xbfb8aa3b, v17
	v_mul_f32_e32 v8, 0xbfb8aa3b, v8
	v_mul_f32_e32 v9, 0xbfb8aa3b, v9
	v_mul_f32_e32 v12, 0xbfb8aa3b, v12
	v_mul_f32_e32 v13, 0xbfb8aa3b, v13
	v_mul_f32_e32 v10, 0xbfb8aa3b, v10
	v_mul_f32_e32 v11, 0xbfb8aa3b, v11
	v_exp_f32_e32 v14, v14
	v_exp_f32_e32 v15, v15
	v_exp_f32_e32 v8, v8
	v_exp_f32_e32 v9, v9
	v_exp_f32_e32 v12, v12
	v_exp_f32_e32 v13, v13
	v_exp_f32_e32 v10, v10
	v_exp_f32_e32 v11, v11
	v_add_f32_e32 v14, 1.0, v14
	v_add_f32_e32 v15, 1.0, v15
	v_add_f32_e32 v8, 1.0, v8
	v_add_f32_e32 v9, 1.0, v9
	v_add_f32_e32 v12, 1.0, v12
	v_add_f32_e32 v13, 1.0, v13
	v_add_f32_e32 v10, 1.0, v10
	v_add_f32_e32 v11, 1.0, v11
	v_rcp_f32_e32 v16, v14
	v_rcp_f32_e32 v17, v15
	v_rcp_f32_e32 v8, v8
	v_rcp_f32_e32 v9, v9
	v_rcp_f32_e32 v12, v12
	v_rcp_f32_e32 v13, v13
	v_rcp_f32_e32 v10, v10
	v_rcp_f32_e32 v11, v11

; __device__ __forceinline__ float sigmoidf_(float x) { return __builtin_amdgcn_rcpf(1.0f + __expf(-x)); }
; __device__ __forceinline__ void phase3(const P3Args& A, unsigned char* lds, int tid, int wave, int lane) {
;     ...
;             const int task = tid + (rep & 7) * 512, tok = task >> 5, c8 = (task & 31) * 8, t = t0 + tok;
;             const u32x4 pc = *(const u32x4*)(A.Rb + (size_t)t * RW + 1536 + c8);
;             u32x4 pp = (u32x4){0u, 0u, 0u, 0u};
;             if (t % SEQ) pp = *(const u32x4*)(A.Rb + (size_t)(t - 1) * RW + 1536 + c8);
;             const f32x4 m0 = *(const f32x4*)(A.mu + 1536 + c8), m1 = *(const f32x4*)(A.mu + 1536 + c8 + 4);
;             const unsigned pcw[4] = {pc.x, pc.y, pc.z, pc.w}, ppw[4] = {pp.x, pp.y, pp.z, pp.w};
;             float x[8];
; #pragma unroll
;             for (int i = 0; i < 4; ++i) {
;                 const float c_lo = __uint_as_float(pcw[i] << 16), c_hi = __uint_as_float(pcw[i] & 0xffff0000u), p_lo = __uint_as_float(ppw[i] << 16), p_hi = __uint_as_float(ppw[i] & 0xffff0000u);
;                 const float mlo = (i < 2) ? m0[2 * i] : m1[2 * i - 4], mhi = (i < 2) ? m0[2 * i + 1] : m1[2 * i - 3];
;                 x[2 * i] = c_lo + (p_lo - c_lo) * mlo; x[2 * i + 1] = c_hi + (p_hi - c_hi) * mhi;
;             }
;             if (c8 < 64) {
; #pragma unroll
;                 for (int i = 0; i < 8; ++i) { const float e = __expf(-2.0f * fabsf(x[i])); const float th = (1.0f - e) * __builtin_amdgcn_rcpf(1.0f + e); x[i] = copysignf(th, x[i]); }
;             } else if (c8 >= 128) {
; #pragma unroll
;                 for (int i = 0; i < 8; ++i) x[i] = sigmoidf_(x[i]);
;             }
.Lp3a_r3:
	v_add_u32_e32 v8, 0x600, v117
	v_ashrrev_i32_e32 v18, 5, v8
	s_waitcnt vmcnt(8)
	v_mov_b32_e32 v8, v152
	v_mov_b32_e32 v9, v153
	v_mov_b32_e32 v10, v154
	v_mov_b32_e32 v11, v155
	v_mov_b32_e32 v12, v156
	v_mov_b32_e32 v13, v157
	v_mov_b32_e32 v14, v158
	v_mov_b32_e32 v15, v159
	v_lshlrev_b32_e32 v16, 16, v8
	v_and_b32_e32 v17, 0xffff0000, v8
	v_lshlrev_b32_e32 v20, 16, v12
	v_and_b32_e32 v21, 0xffff0000, v12
	v_lshlrev_b32_e32 v8, 16, v9
	v_and_b32_e32 v9, 0xffff0000, v9
	v_lshlrev_b32_e32 v12, 16, v13
	v_and_b32_e32 v13, 0xffff0000, v13
	v_pk_add_f32 v[20:21], v[20:21], v[16:17] neg_lo:[0,1] neg_hi:[0,1]
	v_pk_add_f32 v[12:13], v[12:13], v[8:9] neg_lo:[0,1] neg_hi:[0,1]
	v_pk_fma_f32 v[16:17], v[4:5], v[20:21], v[16:17]
	v_pk_fma_f32 v[8:9], v[6:7], v[12:13], v[8:9]
	v_lshlrev_b32_e32 v12, 16, v10
	v_and_b32_e32 v13, 0xffff0000, v10
	v_lshlrev_b32_e32 v20, 16, v14
	v_and_b32_e32 v21, 0xffff0000, v14
	v_lshlrev_b32_e32 v10, 16, v11
	v_and_b32_e32 v11, 0xffff0000, v11
	v_lshlrev_b32_e32 v14, 16, v15
	v_and_b32_e32 v15, 0xffff0000, v15
	v_pk_add_f32 v[20:21], v[20:21], v[12:13] neg_lo:[0,1] neg_hi:[0,1]
	v_pk_add_f32 v[14:15], v[14:15], v[10:11] neg_lo:[0,1] neg_hi:[0,1]
	v_pk_fma_f32 v[12:13], v[0:1], v[20:21], v[12:13]
	v_pk_fma_f32 v[10:11], v[2:3], v[14:15], v[10:11]
	s_and_saveexec_b64 s[0:1], vcc
	s_xor_b64 s[0:1], exec, s[0:1]
	s_cbranch_execz .Lp3a_319_r3
	s_mov_b64 s[4:5], exec
	v_readlane_b32 s8, v241, 61
	v_readlane_b32 s9, v241, 62
	s_and_b64 s[8:9], s[4:5], s[8:9]
	s_mov_b64 exec, s[8:9]
	s_cbranch_execz .Lp3a_318_r3
	v_mul_f32_e32 v14, 0xbfb8aa3b, v16
	v_mul_f32_e32 v15, 0xbfb8aa3b, v17
	v_mul_f32_e32 v8, 0xbfb8aa3b, v8
	v_mul_f32_e32 v9, 0xbfb8aa3b, v9
	v_mul_f32_e32 v12, 0xbfb8aa3b, v12
	v_mul_f32_e32 v13, 0xbfb8aa3b, v13
	v_mul_f32_e32 v10, 0xbfb8aa3b, v10
	v_mul_f32_e32 v11, 0xbfb8aa3b, v11
	v_exp_f32_e32 v14, v14
	v_exp_f32_e32 v15, v15
	v_exp_f32_e32 v8, v8
	v_exp_f32_e32 v9, v9
	v_exp_f32_e32 v12, v12
	v_exp_f32_e32 v13, v13
	v_exp_f32_e32 v10, v10
	v_exp_f32_e32 v11, v11
	v_add_f32_e32 v14, 1.0, v14
	v_add_f32_e32 v15, 1.0, v15
	v_add_f32_e32 v8, 1.0, v8
	v_add_f32_e32 v9, 1.0, v9
	v_add_f32_e32 v12, 1.0, v12
	v_add_f32_e32 v13, 1.0, v13
	v_add_f32_e32 v10, 1.0, v10
	v_add_f32_e32 v11, 1.0, v11
	v_rcp_f32_e32 v16, v14
	v_rcp_f32_e32 v17, v15
	v_rcp_f32_e32 v8, v8
	v_rcp_f32_e32 v9, v9
	v_rcp_f32_e32 v12, v12
	v_rcp_f32_e32 v13, v13
	v_rcp_f32_e32 v10, v10
	v_rcp_f32_e32 v11, v11

; __device__ __forceinline__ float sigmoidf_(float x) { return __builtin_amdgcn_rcpf(1.0f + __expf(-x)); }
; __device__ __forceinline__ void phase3(const P3Args& A, unsigned char* lds, int tid, int wave, int lane) {
;     ...
;             const int task = tid + (rep & 7) * 512, tok = task >> 5, c8 = (task & 31) * 8, t = t0 + tok;
;             const u32x4 pc = *(const u32x4*)(A.Rb + (size_t)t * RW + 1536 + c8);
;             u32x4 pp = (u32x4){0u, 0u, 0u, 0u};
;             if (t % SEQ) pp = *(const u32x4*)(A.Rb + (size_t)(t - 1) * RW + 1536 + c8);
;             const f32x4 m0 = *(const f32x4*)(A.mu + 1536 + c8), m1 = *(const f32x4*)(A.mu + 1536 + c8 + 4);
;             const unsigned pcw[4] = {pc.x, pc.y, pc.z, pc.w}, ppw[4] = {pp.x, pp.y, pp.z, pp.w};
;             float x[8];
; #pragma unroll
;             for (int i = 0; i < 4; ++i) {
;                 const float c_lo = __uint_as_float(pcw[i] << 16), c_hi = __uint_as_float(pcw[i] & 0xffff0000u), p_lo = __uint_as_float(ppw[i] << 16), p_hi = __uint_as_float(ppw[i] & 0xffff0000u);
;                 const float mlo = (i < 2) ? m0[2 * i] : m1[2 * i - 4], mhi = (i < 2) ? m0[2 * i + 1] : m1[2 * i - 3];
;                 x[2 * i] = c_lo + (p_lo - c_lo) * mlo; x[2 * i + 1] = c_hi + (p_hi - c_hi) * mhi;
;             }
;             if (c8 < 64) {
; #pragma unroll
;                 for (int i = 0; i < 8; ++i) { const float e = __expf(-2.0f * fabsf(x[i])); const float th = (1.0f - e) * __builtin_amdgcn_rcpf(1.0f + e); x[i] = copysignf(th, x[i]); }
;             } else if (c8 >= 128) {
; #pragma unroll
;                 for (int i = 0; i < 8; ++i) x[i] = sigmoidf_(x[i]);
;             }
.Lp3a_r4:
	v_add_u32_e32 v8, 0x800, v117
	v_ashrrev_i32_e32 v18, 5, v8
	s_waitcnt vmcnt(6)
	v_mov_b32_e32 v8, v160
	v_mov_b32_e32 v9, v161
	v_mov_b32_e32 v10, v162
	v_mov_b32_e32 v11, v163
	v_mov_b32_e32 v12, v164
	v_mov_b32_e32 v13, v165
	v_mov_b32_e32 v14, v166
	v_mov_b32_e32 v15, v167
	v_lshlrev_b32_e32 v16, 16, v8
	v_and_b32_e32 v17, 0xffff0000, v8
	v_lshlrev_b32_e32 v20, 16, v12
	v_and_b32_e32 v21, 0xffff0000, v12
	v_lshlrev_b32_e32 v8, 16, v9
	v_and_b32_e32 v9, 0xffff0000, v9
	v_lshlrev_b32_e32 v12, 16, v13
	v_and_b32_e32 v13, 0xffff0000, v13
	v_pk_add_f32 v[20:21], v[20:21], v[16:17] neg_lo:[0,1] neg_hi:[0,1]
	v_pk_add_f32 v[12:13], v[12:13], v[8:9] neg_lo:[0,1] neg_hi:[0,1]
	v_pk_fma_f32 v[16:17], v[4:5], v[20:21], v[16:17]
	v_pk_fma_f32 v[8:9], v[6:7], v[12:13], v[8:9]
	v_lshlrev_b32_e32 v12, 16, v10
	v_and_b32_e32 v13, 0xffff0000, v10
	v_lshlrev_b32_e32 v20, 16, v14
	v_and_b32_e32 v21, 0xffff0000, v14
	v_lshlrev_b32_e32 v10, 16, v11
	v_and_b32_e32 v11, 0xffff0000, v11
	v_lshlrev_b32_e32 v14, 16, v15
	v_and_b32_e32 v15, 0xffff0000, v15
	v_pk_add_f32 v[20:21], v[20:21], v[12:13] neg_lo:[0,1] neg_hi:[0,1]
	v_pk_add_f32 v[14:15], v[14:15], v[10:11] neg_lo:[0,1] neg_hi:[0,1]
	v_pk_fma_f32 v[12:13], v[0:1], v[20:21], v[12:13]
	v_pk_fma_f32 v[10:11], v[2:3], v[14:15], v[10:11]
	s_and_saveexec_b64 s[0:1], vcc
	s_xor_b64 s[0:1], exec, s[0:1]
	s_cbranch_execz .Lp3a_319_r4
	s_mov_b64 s[4:5], exec
	v_readlane_b32 s8, v241, 61
	v_readlane_b32 s9, v241, 62
	s_and_b64 s[8:9], s[4:5], s[8:9]
	s_mov_b64 exec, s[8:9]
	s_cbranch_execz .Lp3a_318_r4
	v_mul_f32_e32 v14, 0xbfb8aa3b, v16
	v_mul_f32_e32 v15, 0xbfb8aa3b, v17
	v_mul_f32_e32 v8, 0xbfb8aa3b, v8
	v_mul_f32_e32 v9, 0xbfb8aa3b, v9
	v_mul_f32_e32 v12, 0xbfb8aa3b, v12
	v_mul_f32_e32 v13, 0xbfb8aa3b, v13
	v_mul_f32_e32 v10, 0xbfb8aa3b, v10
	v_mul_f32_e32 v11, 0xbfb8aa3b, v11
	v_exp_f32_e32 v14, v14
	v_exp_f32_e32 v15, v15
	v_exp_f32_e32 v8, v8
	v_exp_f32_e32 v9, v9
	v_exp_f32_e32 v12, v12
	v_exp_f32_e32 v13, v13
	v_exp_f32_e32 v10, v10
	v_exp_f32_e32 v11, v11
	v_add_f32_e32 v14, 1.0, v14
	v_add_f32_e32 v15, 1.0, v15
	v_add_f32_e32 v8, 1.0, v8
	v_add_f32_e32 v9, 1.0, v9
	v_add_f32_e32 v12, 1.0, v12
	v_add_f32_e32 v13, 1.0, v13
	v_add_f32_e32 v10, 1.0, v10
	v_add_f32_e32 v11, 1.0, v11
	v_rcp_f32_e32 v16, v14
	v_rcp_f32_e32 v17, v15
	v_rcp_f32_e32 v8, v8
	v_rcp_f32_e32 v9, v9
	v_rcp_f32_e32 v12, v12
	v_rcp_f32_e32 v13, v13
	v_rcp_f32_e32 v10, v10
	v_rcp_f32_e32 v11, v11

; __device__ __forceinline__ float sigmoidf_(float x) { return __builtin_amdgcn_rcpf(1.0f + __expf(-x)); }
; __device__ __forceinline__ void phase3(const P3Args& A, unsigned char* lds, int tid, int wave, int lane) {
;     ...
;             const int task = tid + (rep & 7) * 512, tok = task >> 5, c8 = (task & 31) * 8, t = t0 + tok;
;             const u32x4 pc = *(const u32x4*)(A.Rb + (size_t)t * RW + 1536 + c8);
;             u32x4 pp = (u32x4){0u, 0u, 0u, 0u};
;             if (t % SEQ) pp = *(const u32x4*)(A.Rb + (size_t)(t - 1) * RW + 1536 + c8);
;             const f32x4 m0 = *(const f32x4*)(A.mu + 1536 + c8), m1 = *(const f32x4*)(A.mu + 1536 + c8 + 4);
;             const unsigned pcw[4] = {pc.x, pc.y, pc.z, pc.w}, ppw[4] = {pp.x, pp.y, pp.z, pp.w};
;             float x[8];
; #pragma unroll
;             for (int i = 0; i < 4; ++i) {
;                 const float c_lo = __uint_as_float(pcw[i] << 16), c_hi = __uint_as_float(pcw[i] & 0xffff0000u), p_lo = __uint_as_float(ppw[i] << 16), p_hi = __uint_as_float(ppw[i] & 0xffff0000u);
;                 const float mlo = (i < 2) ? m0[2 * i] : m1[2 * i - 4], mhi = (i < 2) ? m0[2 * i + 1] : m1[2 * i - 3];
;                 x[2 * i] = c_lo + (p_lo - c_lo) * mlo; x[2 * i + 1] = c_hi + (p_hi - c_hi) * mhi;
;             }
;             if (c8 < 64) {
; #pragma unroll
;                 for (int i = 0; i < 8; ++i) { const float e = __expf(-2.0f * fabsf(x[i])); const float th = (1.0f - e) * __builtin_amdgcn_rcpf(1.0f + e); x[i] = copysignf(th, x[i]); }
;             } else if (c8 >= 128) {
; #pragma unroll
;                 for (int i = 0; i < 8; ++i) x[i] = sigmoidf_(x[i]);
;             }
.Lp3a_r5:
	v_add_u32_e32 v8, 0xa00, v117
	v_ashrrev_i32_e32 v18, 5, v8
	s_waitcnt vmcnt(4)
	v_mov_b32_e32 v8, v168
	v_mov_b32_e32 v9, v169
	v_mov_b32_e32 v10, v170
	v_mov_b32_e32 v11, v171
	v_mov_b32_e32 v12, v172
	v_mov_b32_e32 v13, v173
	v_mov_b32_e32 v14, v174
	v_mov_b32_e32 v15, v175
	v_lshlrev_b32_e32 v16, 16, v8
	v_and_b32_e32 v17, 0xffff0000, v8
	v_lshlrev_b32_e32 v20, 16, v12
	v_and_b32_e32 v21, 0xffff0000, v12
	v_lshlrev_b32_e32 v8, 16, v9
	v_and_b32_e32 v9, 0xffff0000, v9
	v_lshlrev_b32_e32 v12, 16, v13
	v_and_b32_e32 v13, 0xffff0000, v13
	v_pk_add_f32 v[20:21], v[20:21], v[16:17] neg_lo:[0,1] neg_hi:[0,1]
	v_pk_add_f32 v[12:13], v[12:13], v[8:9] neg_lo:[0,1] neg_hi:[0,1]
	v_pk_fma_f32 v[16:17], v[4:5], v[20:21], v[16:17]
	v_pk_fma_f32 v[8:9], v[6:7], v[12:13], v[8:9]
	v_lshlrev_b32_e32 v12, 16, v10
	v_and_b32_e32 v13, 0xffff0000, v10
	v_lshlrev_b32_e32 v20, 16, v14
	v_and_b32_e32 v21, 0xffff0000, v14
	v_lshlrev_b32_e32 v10, 16, v11
	v_and_b32_e32 v11, 0xffff0000, v11
	v_lshlrev_b32_e32 v14, 16, v15
	v_and_b32_e32 v15, 0xffff0000, v15
	v_pk_add_f32 v[20:21], v[20:21], v[12:13] neg_lo:[0,1] neg_hi:[0,1]
	v_pk_add_f32 v[14:15], v[14:15], v[10:11] neg_lo:[0,1] neg_hi:[0,1]
	v_pk_fma_f32 v[12:13], v[0:1], v[20:21], v[12:13]
	v_pk_fma_f32 v[10:11], v[2:3], v[14:15], v[10:11]
	s_and_saveexec_b64 s[0:1], vcc
	s_xor_b64 s[0:1], exec, s[0:1]
	s_cbranch_execz .Lp3a_319_r5
	s_mov_b64 s[4:5], exec
	v_readlane_b32 s8, v241, 61
	v_readlane_b32 s9, v241, 62
	s_and_b64 s[8:9], s[4:5], s[8:9]
	s_mov_b64 exec, s[8:9]
	s_cbranch_execz .Lp3a_318_r5
	v_mul_f32_e32 v14, 0xbfb8aa3b, v16
	v_mul_f32_e32 v15, 0xbfb8aa3b, v17
	v_mul_f32_e32 v8, 0xbfb8aa3b, v8
	v_mul_f32_e32 v9, 0xbfb8aa3b, v9
	v_mul_f32_e32 v12, 0xbfb8aa3b, v12
	v_mul_f32_e32 v13, 0xbfb8aa3b, v13
	v_mul_f32_e32 v10, 0xbfb8aa3b, v10
	v_mul_f32_e32 v11, 0xbfb8aa3b, v11
	v_exp_f32_e32 v14, v14
	v_exp_f32_e32 v15, v15
	v_exp_f32_e32 v8, v8
	v_exp_f32_e32 v9, v9
	v_exp_f32_e32 v12, v12
	v_exp_f32_e32 v13, v13
	v_exp_f32_e32 v10, v10
	v_exp_f32_e32 v11, v11
	v_add_f32_e32 v14, 1.0, v14
	v_add_f32_e32 v15, 1.0, v15
	v_add_f32_e32 v8, 1.0, v8
	v_add_f32_e32 v9, 1.0, v9
	v_add_f32_e32 v12, 1.0, v12
	v_add_f32_e32 v13, 1.0, v13
	v_add_f32_e32 v10, 1.0, v10
	v_add_f32_e32 v11, 1.0, v11
	v_rcp_f32_e32 v16, v14
	v_rcp_f32_e32 v17, v15
	v_rcp_f32_e32 v8, v8
	v_rcp_f32_e32 v9, v9
	v_rcp_f32_e32 v12, v12
	v_rcp_f32_e32 v13, v13
	v_rcp_f32_e32 v10, v10
	v_rcp_f32_e32 v11, v11

; __device__ __forceinline__ float sigmoidf_(float x) { return __builtin_amdgcn_rcpf(1.0f + __expf(-x)); }
; __device__ __forceinline__ void phase3(const P3Args& A, unsigned char* lds, int tid, int wave, int lane) {
;     ...
;             const int task = tid + (rep & 7) * 512, tok = task >> 5, c8 = (task & 31) * 8, t = t0 + tok;
;             const u32x4 pc = *(const u32x4*)(A.Rb + (size_t)t * RW + 1536 + c8);
;             u32x4 pp = (u32x4){0u, 0u, 0u, 0u};
;             if (t % SEQ) pp = *(const u32x4*)(A.Rb + (size_t)(t - 1) * RW + 1536 + c8);
;             const f32x4 m0 = *(const f32x4*)(A.mu + 1536 + c8), m1 = *(const f32x4*)(A.mu + 1536 + c8 + 4);
;             const unsigned pcw[4] = {pc.x, pc.y, pc.z, pc.w}, ppw[4] = {pp.x, pp.y, pp.z, pp.w};
;             float x[8];
; #pragma unroll
;             for (int i = 0; i < 4; ++i) {
;                 const float c_lo = __uint_as_float(pcw[i] << 16), c_hi = __uint_as_float(pcw[i] & 0xffff0000u), p_lo = __uint_as_float(ppw[i] << 16), p_hi = __uint_as_float(ppw[i] & 0xffff0000u);
;                 const float mlo = (i < 2) ? m0[2 * i] : m1[2 * i - 4], mhi = (i < 2) ? m0[2 * i + 1] : m1[2 * i - 3];
;                 x[2 * i] = c_lo + (p_lo - c_lo) * mlo; x[2 * i + 1] = c_hi + (p_hi - c_hi) * mhi;
;             }
;             if (c8 < 64) {
; #pragma unroll
;                 for (int i = 0; i < 8; ++i) { const float e = __expf(-2.0f * fabsf(x[i])); const float th = (1.0f - e) * __builtin_amdgcn_rcpf(1.0f + e); x[i] = copysignf(th, x[i]); }
;             } else if (c8 >= 128) {
; #pragma unroll
;                 for (int i = 0; i < 8; ++i) x[i] = sigmoidf_(x[i]);
;             }
.Lp3a_r6:
	v_add_u32_e32 v8, 0xc00, v117
	v_ashrrev_i32_e32 v18, 5, v8
	s_waitcnt vmcnt(2)
	v_mov_b32_e32 v8, v176
	v_mov_b32_e32 v9, v177
	v_mov_b32_e32 v10, v178
	v_mov_b32_e32 v11, v179
	v_mov_b32_e32 v12, v180
	v_mov_b32_e32 v13, v181
	v_mov_b32_e32 v14, v182
	v_mov_b32_e32 v15, v183
	v_lshlrev_b32_e32 v16, 16, v8
	v_and_b32_e32 v17, 0xffff0000, v8
	v_lshlrev_b32_e32 v20, 16, v12
	v_and_b32_e32 v21, 0xffff0000, v12
	v_lshlrev_b32_e32 v8, 16, v9
	v_and_b32_e32 v9, 0xffff0000, v9
	v_lshlrev_b32_e32 v12, 16, v13
	v_and_b32_e32 v13, 0xffff0000, v13
	v_pk_add_f32 v[20:21], v[20:21], v[16:17] neg_lo:[0,1] neg_hi:[0,1]
	v_pk_add_f32 v[12:13], v[12:13], v[8:9] neg_lo:[0,1] neg_hi:[0,1]
	v_pk_fma_f32 v[16:17], v[4:5], v[20:21], v[16:17]
	v_pk_fma_f32 v[8:9], v[6:7], v[12:13], v[8:9]
	v_lshlrev_b32_e32 v12, 16, v10
	v_and_b32_e32 v13, 0xffff0000, v10
	v_lshlrev_b32_e32 v20, 16, v14
	v_and_b32_e32 v21, 0xffff0000, v14
	v_lshlrev_b32_e32 v10, 16, v11
	v_and_b32_e32 v11, 0xffff0000, v11
	v_lshlrev_b32_e32 v14, 16, v15
	v_and_b32_e32 v15, 0xffff0000, v15
	v_pk_add_f32 v[20:21], v[20:21], v[12:13] neg_lo:[0,1] neg_hi:[0,1]
	v_pk_add_f32 v[14:15], v[14:15], v[10:11] neg_lo:[0,1] neg_hi:[0,1]
	v_pk_fma_f32 v[12:13], v[0:1], v[20:21], v[12:13]
	v_pk_fma_f32 v[10:11], v[2:3], v[14:15], v[10:11]
	s_and_saveexec_b64 s[0:1], vcc
	s_xor_b64 s[0:1], exec, s[0:1]
	s_cbranch_execz .Lp3a_319_r6
	s_mov_b64 s[4:5], exec
	v_readlane_b32 s8, v241, 61
	v_readlane_b32 s9, v241, 62
	s_and_b64 s[8:9], s[4:5], s[8:9]
	s_mov_b64 exec, s[8:9]
	s_cbranch_execz .Lp3a_318_r6
	v_mul_f32_e32 v14, 0xbfb8aa3b, v16
	v_mul_f32_e32 v15, 0xbfb8aa3b, v17
	v_mul_f32_e32 v8, 0xbfb8aa3b, v8
	v_mul_f32_e32 v9, 0xbfb8aa3b, v9
	v_mul_f32_e32 v12, 0xbfb8aa3b, v12
	v_mul_f32_e32 v13, 0xbfb8aa3b, v13
	v_mul_f32_e32 v10, 0xbfb8aa3b, v10
	v_mul_f32_e32 v11, 0xbfb8aa3b, v11
	v_exp_f32_e32 v14, v14
	v_exp_f32_e32 v15, v15
	v_exp_f32_e32 v8, v8
	v_exp_f32_e32 v9, v9
	v_exp_f32_e32 v12, v12
	v_exp_f32_e32 v13, v13
	v_exp_f32_e32 v10, v10
	v_exp_f32_e32 v11, v11
	v_add_f32_e32 v14, 1.0, v14
	v_add_f32_e32 v15, 1.0, v15
	v_add_f32_e32 v8, 1.0, v8
	v_add_f32_e32 v9, 1.0, v9
	v_add_f32_e32 v12, 1.0, v12
	v_add_f32_e32 v13, 1.0, v13
	v_add_f32_e32 v10, 1.0, v10
	v_add_f32_e32 v11, 1.0, v11
	v_rcp_f32_e32 v16, v14
	v_rcp_f32_e32 v17, v15
	v_rcp_f32_e32 v8, v8
	v_rcp_f32_e32 v9, v9
	v_rcp_f32_e32 v12, v12
	v_rcp_f32_e32 v13, v13
	v_rcp_f32_e32 v10, v10
	v_rcp_f32_e32 v11, v11

; __device__ __forceinline__ float sigmoidf_(float x) { return __builtin_amdgcn_rcpf(1.0f + __expf(-x)); }
; __device__ __forceinline__ void phase3(const P3Args& A, unsigned char* lds, int tid, int wave, int lane) {
;     ...
;             const int task = tid + (rep & 7) * 512, tok = task >> 5, c8 = (task & 31) * 8, t = t0 + tok;
;             const u32x4 pc = *(const u32x4*)(A.Rb + (size_t)t * RW + 1536 + c8);
;             u32x4 pp = (u32x4){0u, 0u, 0u, 0u};
;             if (t % SEQ) pp = *(const u32x4*)(A.Rb + (size_t)(t - 1) * RW + 1536 + c8);
;             const f32x4 m0 = *(const f32x4*)(A.mu + 1536 + c8), m1 = *(const f32x4*)(A.mu + 1536 + c8 + 4);
;             const unsigned pcw[4] = {pc.x, pc.y, pc.z, pc.w}, ppw[4] = {pp.x, pp.y, pp.z, pp.w};
;             float x[8];
; #pragma unroll
;             for (int i = 0; i < 4; ++i) {
;                 const float c_lo = __uint_as_float(pcw[i] << 16), c_hi = __uint_as_float(pcw[i] & 0xffff0000u), p_lo = __uint_as_float(ppw[i] << 16), p_hi = __uint_as_float(ppw[i] & 0xffff0000u);
;                 const float mlo = (i < 2) ? m0[2 * i] : m1[2 * i - 4], mhi = (i < 2) ? m0[2 * i + 1] : m1[2 * i - 3];
;                 x[2 * i] = c_lo + (p_lo - c_lo) * mlo; x[2 * i + 1] = c_hi + (p_hi - c_hi) * mhi;
;             }
;             if (c8 < 64) {
; #pragma unroll
;                 for (int i = 0; i < 8; ++i) { const float e = __expf(-2.0f * fabsf(x[i])); const float th = (1.0f - e) * __builtin_amdgcn_rcpf(1.0f + e); x[i] = copysignf(th, x[i]); }
;             } else if (c8 >= 128) {
; #pragma unroll
;                 for (int i = 0; i < 8; ++i) x[i] = sigmoidf_(x[i]);
;             }
.Lp3a_r7:
	v_add_u32_e32 v8, 0xe00, v117
	v_ashrrev_i32_e32 v18, 5, v8
	s_waitcnt vmcnt(0)
	v_mov_b32_e32 v8, v184
	v_mov_b32_e32 v9, v185
	v_mov_b32_e32 v10, v186
	v_mov_b32_e32 v11, v187
	v_mov_b32_e32 v12, v188
	v_mov_b32_e32 v13, v189
	v_mov_b32_e32 v14, v190
	v_mov_b32_e32 v15, v191
	v_lshlrev_b32_e32 v16, 16, v8
	v_and_b32_e32 v17, 0xffff0000, v8
	v_lshlrev_b32_e32 v20, 16, v12
	v_and_b32_e32 v21, 0xffff0000, v12
	v_lshlrev_b32_e32 v8, 16, v9
	v_and_b32_e32 v9, 0xffff0000, v9
	v_lshlrev_b32_e32 v12, 16, v13
	v_and_b32_e32 v13, 0xffff0000, v13
	v_pk_add_f32 v[20:21], v[20:21], v[16:17] neg_lo:[0,1] neg_hi:[0,1]
	v_pk_add_f32 v[12:13], v[12:13], v[8:9] neg_lo:[0,1] neg_hi:[0,1]
	v_pk_fma_f32 v[16:17], v[4:5], v[20:21], v[16:17]
	v_pk_fma_f32 v[8:9], v[6:7], v[12:13], v[8:9]
	v_lshlrev_b32_e32 v12, 16, v10
	v_and_b32_e32 v13, 0xffff0000, v10
	v_lshlrev_b32_e32 v20, 16, v14
	v_and_b32_e32 v21, 0xffff0000, v14
	v_lshlrev_b32_e32 v10, 16, v11
	v_and_b32_e32 v11, 0xffff0000, v11
	v_lshlrev_b32_e32 v14, 16, v15
	v_and_b32_e32 v15, 0xffff0000, v15
	v_pk_add_f32 v[20:21], v[20:21], v[12:13] neg_lo:[0,1] neg_hi:[0,1]
	v_pk_add_f32 v[14:15], v[14:15], v[10:11] neg_lo:[0,1] neg_hi:[0,1]
	v_pk_fma_f32 v[12:13], v[0:1], v[20:21], v[12:13]
	v_pk_fma_f32 v[10:11], v[2:3], v[14:15], v[10:11]
	s_and_saveexec_b64 s[0:1], vcc
	s_xor_b64 s[0:1], exec, s[0:1]
	s_cbranch_execz .Lp3a_319_r7
	s_mov_b64 s[4:5], exec
	v_readlane_b32 s8, v241, 61
	v_readlane_b32 s9, v241, 62
	s_and_b64 s[8:9], s[4:5], s[8:9]
	s_mov_b64 exec, s[8:9]
	s_cbranch_execz .Lp3a_318_r7
	v_mul_f32_e32 v14, 0xbfb8aa3b, v16
	v_mul_f32_e32 v15, 0xbfb8aa3b, v17
	v_mul_f32_e32 v8, 0xbfb8aa3b, v8
	v_mul_f32_e32 v9, 0xbfb8aa3b, v9
	v_mul_f32_e32 v12, 0xbfb8aa3b, v12
	v_mul_f32_e32 v13, 0xbfb8aa3b, v13
	v_mul_f32_e32 v10, 0xbfb8aa3b, v10
	v_mul_f32_e32 v11, 0xbfb8aa3b, v11
	v_exp_f32_e32 v14, v14
	v_exp_f32_e32 v15, v15
	v_exp_f32_e32 v8, v8
	v_exp_f32_e32 v9, v9
	v_exp_f32_e32 v12, v12
	v_exp_f32_e32 v13, v13
	v_exp_f32_e32 v10, v10
	v_exp_f32_e32 v11, v11
	v_add_f32_e32 v14, 1.0, v14
	v_add_f32_e32 v15, 1.0, v15
	v_add_f32_e32 v8, 1.0, v8
	v_add_f32_e32 v9, 1.0, v9
	v_add_f32_e32 v12, 1.0, v12
	v_add_f32_e32 v13, 1.0, v13
	v_add_f32_e32 v10, 1.0, v10
	v_add_f32_e32 v11, 1.0, v11
	v_rcp_f32_e32 v16, v14
	v_rcp_f32_e32 v17, v15
	v_rcp_f32_e32 v8, v8
	v_rcp_f32_e32 v9, v9
	v_rcp_f32_e32 v12, v12
	v_rcp_f32_e32 v13, v13
	v_rcp_f32_e32 v10, v10
	v_rcp_f32_e32 v11, v11
